# load balance: P0b W-quant rows start at (gw + NGW/2) mod NGW, P2 ctx S5 states computed by blocks 128..255 (off the 9-item LRU blocks)
# speedup vs baseline: 1.0068x; 1.0011x over previous
; __device__ __forceinline__ void phase_norm(Frame& F, const Params& p, int which) {
;     ...
;         for (int rw0 = gw; rw0 < INW + D; rw0 += NGW) {
;             const bool isq = rw0 >= INW; const int rw = isq ? rw0 - INW : rw0;
;             const u32x4* src = (const u32x4*)((const bf16*)(F.ws + (isq ? WS_WQ : WS_WIN)) + (size_t)rw * D) + F.lane;
;             u32x2* dst = (u32x2*)(F.ws + (isq ? WS_WQI8 : WS_WINI8) + (size_t)rw * D) + F.lane;
.LBB0_309:
	s_cmpk_gt_i32 s60, 0x23ff
	s_cbranch_scc1 .LBB0_314
	v_xor_b32_e32 v0, 4, v40
	v_xor_b32_e32 v1, 8, v40
	v_xor_b32_e32 v2, 16, v40
	v_xor_b32_e32 v3, 32, v40
	v_xor_b32_e32 v4, 64, v40
	v_xor_b32_e32 v5, 0x80, v40
	v_cmp_eq_u32_e64 s[4:5], 0, v28
	s_mov_b32 s16, 0x3600000
	s_mov_b32 s17, 0x9000000
	s_mov_b32 s18, 0x42fe0000
	s_mov_b32 s19, 0x40c0c00
	s_mov_b32 s28, 0x18000
	v_mov_b32_e32 v6, 0
	s_lshr_b32 s29, s54, 1
	s_add_i32 s29, s29, s60
	s_cmp_ge_i32 s29, s54
	s_cselect_b32 s12, s54, 0
	s_sub_i32 s29, s29, s12
	s_branch .LBB0_312

; __device__ __forceinline__ void ctx_s5_states(Frame& F) {
;     const int w = F.bx * NWAVES + F.wave; if (w >= 1024) return;
;     const int g = w >> 4, ctile = w & 15, l15 = F.lane & 15, q = F.lane >> 4;
;     const bf16* A = (const bf16*)(F.ws + WS_XC) + (size_t)(g * 16 + l15) * 512 + 8 * q;
;     const bf16* B = (const bf16*)(F.ws + WS_MS) + (size_t)(g * 256 + ctile * 16 + l15) * 512 + 8 * q;
;     f32x4 a0 = {0, 0, 0, 0};
; #pragma unroll
;     for (int ks = 0; ks < 16; ++ks) a0 = __builtin_amdgcn_mfma_f32_16x16x32_bf16(*(const bf16x8*)(A + ks * 32), *(const bf16x8*)(B + ks * 32), a0, 0, 0, 0);
; #pragma unroll
;     for (int r = 0; r < 4; ++r) ((float*)(F.ws + WS_SC))[(size_t)(g * 16 + 4 * q + r) * 256 + ctile * 16 + l15] = a0[r];
; }
.LBB0_658:
	s_sub_i32 s99, s60, 0x400
	s_cmp_gt_u32 s99, 0x3ff
	v_mbcnt_lo_u32_b32 v108, -1, 0
	v_mbcnt_hi_u32_b32 v108, -1, v108
	s_cbranch_scc1 .LBB0_660
	v_ashrrev_i32_e32 v97, 4, v108
	v_bfi_b32 v0, 15, v108, s99
	v_ashrrev_i32_e32 v1, 31, v0
	v_lshlrev_b32_e32 v2, 3, v97
	v_lshlrev_b64 v[0:1], 10, v[0:1]
	v_ashrrev_i32_e32 v3, 31, v2
	v_lshl_add_u64 v[0:1], s[56:57], 0, v[0:1]
	v_lshlrev_b64 v[4:5], 1, v[2:3]
	v_lshl_add_u64 v[0:1], v[0:1], 0, v[4:5]
	s_mov_b64 s[4:5], 0x3e200000
	v_and_b32_e32 v96, 15, v108
	v_lshl_add_u64 v[92:93], v[0:1], 0, s[4:5]
	s_mov_b32 s4, 0x3e200000
	v_lshl_or_b32 v2, s99, 4, v96
	v_add_co_u32_e32 v0, vcc, s4, v0
	v_ashrrev_i32_e32 v3, 31, v2
	s_nop 0
	v_addc_co_u32_e32 v1, vcc, 0, v1, vcc
	v_lshlrev_b64 v[6:7], 10, v[2:3]
	global_load_dwordx4 v[0:3], v[0:1], off
	v_lshl_add_u64 v[6:7], s[6:7], 0, v[6:7]
	v_lshl_add_u64 v[94:95], v[6:7], 0, v[4:5]
	global_load_dwordx4 v[4:7], v[94:95], off
	global_load_dwordx4 v[8:11], v[92:93], off offset:64
	global_load_dwordx4 v[12:15], v[92:93], off offset:128
	global_load_dwordx4 v[16:19], v[94:95], off offset:64
	global_load_dwordx4 v[20:23], v[94:95], off offset:128
	global_load_dwordx4 v[24:27], v[92:93], off offset:192
	global_load_dwordx4 v[28:31], v[92:93], off offset:256
	global_load_dwordx4 v[32:35], v[94:95], off offset:192
	global_load_dwordx4 v[36:39], v[94:95], off offset:256
	global_load_dwordx4 v[40:43], v[92:93], off offset:320
	global_load_dwordx4 v[44:47], v[94:95], off offset:320
	global_load_dwordx4 v[48:51], v[92:93], off offset:384
	global_load_dwordx4 v[52:55], v[94:95], off offset:384
	global_load_dwordx4 v[56:59], v[92:93], off offset:448
	global_load_dwordx4 v[60:63], v[92:93], off offset:512
	global_load_dwordx4 v[64:67], v[94:95], off offset:448
	global_load_dwordx4 v[68:71], v[94:95], off offset:512
	global_load_dwordx4 v[72:75], v[92:93], off offset:576
	global_load_dwordx4 v[76:79], v[92:93], off offset:640
	global_load_dwordx4 v[80:83], v[92:93], off offset:960
	global_load_dwordx4 v[84:87], v[94:95], off offset:960
	s_and_b32 s6, s99, -16
	s_lshl_b32 s7, s99, 6
	s_mov_b64 s[4:5], 0x3e400000
	s_waitcnt vmcnt(0)
	v_mfma_f32_16x16x32_bf16 v[0:3], v[0:3], v[4:7], 0
	global_load_dwordx4 v[4:7], v[94:95], off offset:576
	global_load_dwordx4 v[88:91], v[94:95], off offset:640
	v_mfma_f32_16x16x32_bf16 v[0:3], v[8:11], v[16:19], v[0:3]
	global_load_dwordx4 v[8:11], v[92:93], off offset:704
	global_load_dwordx4 v[16:19], v[92:93], off offset:768
	v_mfma_f32_16x16x32_bf16 v[0:3], v[12:15], v[20:23], v[0:3]
	global_load_dwordx4 v[12:15], v[94:95], off offset:704
	global_load_dwordx4 v[20:23], v[94:95], off offset:768
	v_mfma_f32_16x16x32_bf16 v[0:3], v[24:27], v[32:35], v[0:3]
	global_load_dwordx4 v[24:27], v[92:93], off offset:832
	global_load_dwordx4 v[32:35], v[94:95], off offset:832
	v_mfma_f32_16x16x32_bf16 v[0:3], v[28:31], v[36:39], v[0:3]
	global_load_dwordx4 v[28:31], v[92:93], off offset:896
	global_load_dwordx4 v[36:39], v[94:95], off offset:896
	v_mfma_f32_16x16x32_bf16 v[0:3], v[40:43], v[44:47], v[0:3]
	v_lshl_add_u32 v42, v97, 2, s6
	s_and_b32 s6, s7, 0x3c0
	s_add_u32 s6, s56, s6
	v_mfma_f32_16x16x32_bf16 v[0:3], v[48:51], v[52:55], v[0:3]
	v_mov_b32_e32 v41, 0
	v_lshlrev_b32_e32 v40, 2, v96
	s_addc_u32 s7, s57, 0
	v_mfma_f32_16x16x32_bf16 v[0:3], v[56:59], v[64:67], v[0:3]
	v_ashrrev_i32_e32 v43, 31, v42
	v_or_b32_e32 v44, 3, v42
	v_ashrrev_i32_e32 v45, 31, v44
	v_mfma_f32_16x16x32_bf16 v[0:3], v[60:63], v[68:71], v[0:3]
	s_waitcnt vmcnt(9)
	v_mfma_f32_16x16x32_bf16 v[0:3], v[72:75], v[4:7], v[0:3]
	v_or_b32_e32 v4, 1, v42
	v_or_b32_e32 v6, 2, v42
	v_lshlrev_b64 v[42:43], 10, v[42:43]
	s_waitcnt vmcnt(8)
	v_mfma_f32_16x16x32_bf16 v[0:3], v[76:79], v[88:91], v[0:3]
	v_ashrrev_i32_e32 v5, 31, v4
	v_ashrrev_i32_e32 v7, 31, v6
	v_lshlrev_b64 v[4:5], 10, v[4:5]
	s_waitcnt vmcnt(5)
	v_mfma_f32_16x16x32_bf16 v[0:3], v[8:11], v[12:15], v[0:3]
	v_lshl_add_u64 v[8:9], s[6:7], 0, v[40:41]
	v_lshl_add_u64 v[8:9], v[8:9], 0, s[4:5]
	v_lshlrev_b64 v[6:7], 10, v[6:7]
	s_waitcnt vmcnt(4)
	v_mfma_f32_16x16x32_bf16 v[0:3], v[16:19], v[20:23], v[0:3]
	v_lshlrev_b64 v[10:11], 10, v[44:45]
	v_lshl_add_u64 v[12:13], v[8:9], 0, v[42:43]
	v_lshl_add_u64 v[4:5], v[8:9], 0, v[4:5]
	s_waitcnt vmcnt(2)
	v_mfma_f32_16x16x32_bf16 v[0:3], v[24:27], v[32:35], v[0:3]
	v_lshl_add_u64 v[6:7], v[8:9], 0, v[6:7]
	v_lshl_add_u64 v[8:9], v[8:9], 0, v[10:11]
	s_waitcnt vmcnt(0)
	v_mfma_f32_16x16x32_bf16 v[0:3], v[28:31], v[36:39], v[0:3]
	v_mfma_f32_16x16x32_bf16 v[0:3], v[80:83], v[84:87], v[0:3]
	s_nop 7
	global_store_dword v[12:13], v0, off
	global_store_dword v[4:5], v1, off
	global_store_dword v[6:7], v2, off
	global_store_dword v[8:9], v3, off
